# S0 combined pool projection (WPC) on v_mfma_f32_4x4x1_16b_f32 (f32 operands, f32 accumulate, same k order) with double-buffered row loads, replacing the packed-f32 VALU loop; on top of v63
# baseline (speedup 1.0000x reference)
.LBB0_214:
	s_or_b64 exec, exec, s[4:5]
	s_lshl_b64 s[2:3], s[2:3], 22
	s_waitcnt lgkmcnt(0)
	s_add_u32 s0, s0, s2
	s_addc_u32 s1, s1, s3
	s_lshl_b32 s3, s15, 20
	s_waitcnt vmcnt(0)
	s_add_u32 s0, s0, s3
	s_addc_u32 s1, s1, 0
	v_lshrrev_b32_e32 v1, 6, v128
	v_and_b32_e32 v0, 63, v128
	v_lshl_add_u32 v0, v1, 7, v0
	v_lshlrev_b32_e32 v2, 2, v0
	v_and_b32_e32 v3, 3, v128
	v_lshlrev_b32_e32 v3, 2, v3
	v_mov_b32_e32 v4, 0
	v_mov_b32_e32 v5, 0
	v_mov_b32_e32 v6, 0
	v_mov_b32_e32 v7, 0
	v_mov_b32_e32 v8, 0
	v_mov_b32_e32 v9, 0
	v_mov_b32_e32 v10, 0
	v_mov_b32_e32 v11, 0
	v_mov_b32_e32 v12, 0
	v_mov_b32_e32 v13, 0
	v_mov_b32_e32 v14, 0
	v_mov_b32_e32 v15, 0
	v_mov_b32_e32 v16, 0
	v_mov_b32_e32 v17, 0
	v_mov_b32_e32 v18, 0
	v_mov_b32_e32 v19, 0
	s_mov_b32 s2, 0
	s_barrier
	global_load_dword v20, v2, s[0:1]
	global_load_dword v21, v2, s[0:1] offset:256
	s_add_u32 s0, s0, 0x1000
	s_addc_u32 s1, s1, 0
	global_load_dword v22, v2, s[0:1]
	global_load_dword v23, v2, s[0:1] offset:256
	s_add_u32 s0, s0, 0x1000
	s_addc_u32 s1, s1, 0
	global_load_dword v24, v2, s[0:1]
	global_load_dword v25, v2, s[0:1] offset:256
	s_add_u32 s0, s0, 0x1000
	s_addc_u32 s1, s1, 0
	global_load_dword v26, v2, s[0:1]
	global_load_dword v27, v2, s[0:1] offset:256
	s_add_u32 s0, s0, 0x1000
	s_addc_u32 s1, s1, 0
	global_load_dword v28, v2, s[0:1]
	global_load_dword v29, v2, s[0:1] offset:256
	s_add_u32 s0, s0, 0x1000
	s_addc_u32 s1, s1, 0
	global_load_dword v30, v2, s[0:1]
	global_load_dword v31, v2, s[0:1] offset:256
	s_add_u32 s0, s0, 0x1000
	s_addc_u32 s1, s1, 0
	global_load_dword v32, v2, s[0:1]
	global_load_dword v33, v2, s[0:1] offset:256
	s_add_u32 s0, s0, 0x1000
	s_addc_u32 s1, s1, 0
	global_load_dword v34, v2, s[0:1]
	global_load_dword v35, v2, s[0:1] offset:256
	s_add_u32 s0, s0, 0x1000
	s_addc_u32 s1, s1, 0
	ds_read2_b32 v[66:67], v3 offset0:0 offset1:4
	ds_read2_b32 v[68:69], v3 offset0:8 offset1:12
	ds_read2_b32 v[70:71], v3 offset0:16 offset1:20
	ds_read2_b32 v[72:73], v3 offset0:24 offset1:28
	ds_read2_b32 v[74:75], v3 offset0:32 offset1:36
	ds_read2_b32 v[76:77], v3 offset0:40 offset1:44
	ds_read2_b32 v[78:79], v3 offset0:48 offset1:52
	ds_read2_b32 v[80:81], v3 offset0:56 offset1:60
	v_add_u32_e32 v3, 0x100, v3
.Lmy_wpc_loop:
	global_load_dword v36, v2, s[0:1]
	global_load_dword v37, v2, s[0:1] offset:256
	s_add_u32 s0, s0, 0x1000
	s_addc_u32 s1, s1, 0
	global_load_dword v38, v2, s[0:1]
	global_load_dword v39, v2, s[0:1] offset:256
	s_add_u32 s0, s0, 0x1000
	s_addc_u32 s1, s1, 0
	global_load_dword v40, v2, s[0:1]
	global_load_dword v41, v2, s[0:1] offset:256
	s_add_u32 s0, s0, 0x1000
	s_addc_u32 s1, s1, 0
	global_load_dword v42, v2, s[0:1]
	global_load_dword v43, v2, s[0:1] offset:256
	s_add_u32 s0, s0, 0x1000
	s_addc_u32 s1, s1, 0
	global_load_dword v44, v2, s[0:1]
	global_load_dword v45, v2, s[0:1] offset:256
	s_add_u32 s0, s0, 0x1000
	s_addc_u32 s1, s1, 0
	global_load_dword v46, v2, s[0:1]
	global_load_dword v47, v2, s[0:1] offset:256
	s_add_u32 s0, s0, 0x1000
	s_addc_u32 s1, s1, 0
	global_load_dword v48, v2, s[0:1]
	global_load_dword v49, v2, s[0:1] offset:256
	s_add_u32 s0, s0, 0x1000
	s_addc_u32 s1, s1, 0
	global_load_dword v50, v2, s[0:1]
	global_load_dword v51, v2, s[0:1] offset:256
	s_add_u32 s0, s0, 0x1000
	s_addc_u32 s1, s1, 0
	ds_read2_b32 v[82:83], v3 offset0:0 offset1:4
	ds_read2_b32 v[84:85], v3 offset0:8 offset1:12
	ds_read2_b32 v[86:87], v3 offset0:16 offset1:20
	ds_read2_b32 v[88:89], v3 offset0:24 offset1:28
	ds_read2_b32 v[90:91], v3 offset0:32 offset1:36
	ds_read2_b32 v[92:93], v3 offset0:40 offset1:44
	ds_read2_b32 v[94:95], v3 offset0:48 offset1:52
	ds_read2_b32 v[96:97], v3 offset0:56 offset1:60
	v_add_u32_e32 v3, 0x100, v3
	s_waitcnt vmcnt(16) lgkmcnt(8)
	v_mfma_f32_4x4x1_16b_f32 v[4:7], v66, v20, v[4:7]
	v_mfma_f32_4x4x1_16b_f32 v[12:15], v66, v21, v[12:15]
	v_mfma_f32_4x4x1_16b_f32 v[8:11], v67, v20, v[8:11]
	v_mfma_f32_4x4x1_16b_f32 v[16:19], v67, v21, v[16:19]
	v_mfma_f32_4x4x1_16b_f32 v[4:7], v68, v22, v[4:7]
	v_mfma_f32_4x4x1_16b_f32 v[12:15], v68, v23, v[12:15]
	v_mfma_f32_4x4x1_16b_f32 v[8:11], v69, v22, v[8:11]
	v_mfma_f32_4x4x1_16b_f32 v[16:19], v69, v23, v[16:19]
	v_mfma_f32_4x4x1_16b_f32 v[4:7], v70, v24, v[4:7]
	v_mfma_f32_4x4x1_16b_f32 v[12:15], v70, v25, v[12:15]
	v_mfma_f32_4x4x1_16b_f32 v[8:11], v71, v24, v[8:11]
	v_mfma_f32_4x4x1_16b_f32 v[16:19], v71, v25, v[16:19]
	v_mfma_f32_4x4x1_16b_f32 v[4:7], v72, v26, v[4:7]
	v_mfma_f32_4x4x1_16b_f32 v[12:15], v72, v27, v[12:15]
	v_mfma_f32_4x4x1_16b_f32 v[8:11], v73, v26, v[8:11]
	v_mfma_f32_4x4x1_16b_f32 v[16:19], v73, v27, v[16:19]
	v_mfma_f32_4x4x1_16b_f32 v[4:7], v74, v28, v[4:7]
	v_mfma_f32_4x4x1_16b_f32 v[12:15], v74, v29, v[12:15]
	v_mfma_f32_4x4x1_16b_f32 v[8:11], v75, v28, v[8:11]
	v_mfma_f32_4x4x1_16b_f32 v[16:19], v75, v29, v[16:19]
	v_mfma_f32_4x4x1_16b_f32 v[4:7], v76, v30, v[4:7]
	v_mfma_f32_4x4x1_16b_f32 v[12:15], v76, v31, v[12:15]
	v_mfma_f32_4x4x1_16b_f32 v[8:11], v77, v30, v[8:11]
	v_mfma_f32_4x4x1_16b_f32 v[16:19], v77, v31, v[16:19]
	v_mfma_f32_4x4x1_16b_f32 v[4:7], v78, v32, v[4:7]
	v_mfma_f32_4x4x1_16b_f32 v[12:15], v78, v33, v[12:15]
	v_mfma_f32_4x4x1_16b_f32 v[8:11], v79, v32, v[8:11]
	v_mfma_f32_4x4x1_16b_f32 v[16:19], v79, v33, v[16:19]
	v_mfma_f32_4x4x1_16b_f32 v[4:7], v80, v34, v[4:7]
	v_mfma_f32_4x4x1_16b_f32 v[12:15], v80, v35, v[12:15]
	v_mfma_f32_4x4x1_16b_f32 v[8:11], v81, v34, v[8:11]
	v_mfma_f32_4x4x1_16b_f32 v[16:19], v81, v35, v[16:19]
	s_cmp_eq_u32 s2, 15
	s_cbranch_scc1 .Lmy_wpc_last
	global_load_dword v20, v2, s[0:1]
	global_load_dword v21, v2, s[0:1] offset:256
	s_add_u32 s0, s0, 0x1000
	s_addc_u32 s1, s1, 0
	global_load_dword v22, v2, s[0:1]
	global_load_dword v23, v2, s[0:1] offset:256
	s_add_u32 s0, s0, 0x1000
	s_addc_u32 s1, s1, 0
	global_load_dword v24, v2, s[0:1]
	global_load_dword v25, v2, s[0:1] offset:256
	s_add_u32 s0, s0, 0x1000
	s_addc_u32 s1, s1, 0
	global_load_dword v26, v2, s[0:1]
	global_load_dword v27, v2, s[0:1] offset:256
	s_add_u32 s0, s0, 0x1000
	s_addc_u32 s1, s1, 0
	global_load_dword v28, v2, s[0:1]
	global_load_dword v29, v2, s[0:1] offset:256
	s_add_u32 s0, s0, 0x1000
	s_addc_u32 s1, s1, 0
	global_load_dword v30, v2, s[0:1]
	global_load_dword v31, v2, s[0:1] offset:256
	s_add_u32 s0, s0, 0x1000
	s_addc_u32 s1, s1, 0
	global_load_dword v32, v2, s[0:1]
	global_load_dword v33, v2, s[0:1] offset:256
	s_add_u32 s0, s0, 0x1000
	s_addc_u32 s1, s1, 0
	global_load_dword v34, v2, s[0:1]
	global_load_dword v35, v2, s[0:1] offset:256
	s_add_u32 s0, s0, 0x1000
	s_addc_u32 s1, s1, 0
	ds_read2_b32 v[66:67], v3 offset0:0 offset1:4
	ds_read2_b32 v[68:69], v3 offset0:8 offset1:12
	ds_read2_b32 v[70:71], v3 offset0:16 offset1:20
	ds_read2_b32 v[72:73], v3 offset0:24 offset1:28
	ds_read2_b32 v[74:75], v3 offset0:32 offset1:36
	ds_read2_b32 v[76:77], v3 offset0:40 offset1:44
	ds_read2_b32 v[78:79], v3 offset0:48 offset1:52
	ds_read2_b32 v[80:81], v3 offset0:56 offset1:60
	v_add_u32_e32 v3, 0x100, v3
	s_waitcnt vmcnt(16) lgkmcnt(8)
	s_branch .Lmy_wpc_mmao
.Lmy_wpc_last:
	s_waitcnt vmcnt(0) lgkmcnt(0)
.Lmy_wpc_mmao:
	v_mfma_f32_4x4x1_16b_f32 v[4:7], v82, v36, v[4:7]
	v_mfma_f32_4x4x1_16b_f32 v[12:15], v82, v37, v[12:15]
	v_mfma_f32_4x4x1_16b_f32 v[8:11], v83, v36, v[8:11]
	v_mfma_f32_4x4x1_16b_f32 v[16:19], v83, v37, v[16:19]
	v_mfma_f32_4x4x1_16b_f32 v[4:7], v84, v38, v[4:7]
	v_mfma_f32_4x4x1_16b_f32 v[12:15], v84, v39, v[12:15]
	v_mfma_f32_4x4x1_16b_f32 v[8:11], v85, v38, v[8:11]
	v_mfma_f32_4x4x1_16b_f32 v[16:19], v85, v39, v[16:19]
	v_mfma_f32_4x4x1_16b_f32 v[4:7], v86, v40, v[4:7]
	v_mfma_f32_4x4x1_16b_f32 v[12:15], v86, v41, v[12:15]
	v_mfma_f32_4x4x1_16b_f32 v[8:11], v87, v40, v[8:11]
	v_mfma_f32_4x4x1_16b_f32 v[16:19], v87, v41, v[16:19]
	v_mfma_f32_4x4x1_16b_f32 v[4:7], v88, v42, v[4:7]
	v_mfma_f32_4x4x1_16b_f32 v[12:15], v88, v43, v[12:15]
	v_mfma_f32_4x4x1_16b_f32 v[8:11], v89, v42, v[8:11]
	v_mfma_f32_4x4x1_16b_f32 v[16:19], v89, v43, v[16:19]
	v_mfma_f32_4x4x1_16b_f32 v[4:7], v90, v44, v[4:7]
	v_mfma_f32_4x4x1_16b_f32 v[12:15], v90, v45, v[12:15]
	v_mfma_f32_4x4x1_16b_f32 v[8:11], v91, v44, v[8:11]
	v_mfma_f32_4x4x1_16b_f32 v[16:19], v91, v45, v[16:19]
	v_mfma_f32_4x4x1_16b_f32 v[4:7], v92, v46, v[4:7]
	v_mfma_f32_4x4x1_16b_f32 v[12:15], v92, v47, v[12:15]
	v_mfma_f32_4x4x1_16b_f32 v[8:11], v93, v46, v[8:11]
	v_mfma_f32_4x4x1_16b_f32 v[16:19], v93, v47, v[16:19]
	v_mfma_f32_4x4x1_16b_f32 v[4:7], v94, v48, v[4:7]
	v_mfma_f32_4x4x1_16b_f32 v[12:15], v94, v49, v[12:15]
	v_mfma_f32_4x4x1_16b_f32 v[8:11], v95, v48, v[8:11]
	v_mfma_f32_4x4x1_16b_f32 v[16:19], v95, v49, v[16:19]
	v_mfma_f32_4x4x1_16b_f32 v[4:7], v96, v50, v[4:7]
	v_mfma_f32_4x4x1_16b_f32 v[12:15], v96, v51, v[12:15]
	v_mfma_f32_4x4x1_16b_f32 v[8:11], v97, v50, v[8:11]
	v_mfma_f32_4x4x1_16b_f32 v[16:19], v97, v51, v[16:19]
	s_add_i32 s2, s2, 1
	s_cmp_lt_u32 s2, 16
	s_cbranch_scc1 .Lmy_wpc_loop
	s_nop 7
	s_nop 7
	s_cmpk_lt_u32 s44, 0x80
	s_mov_b32 s0, 0x1880000
	s_cselect_b32 s0, s0, 0x11ac0000
	s_add_u32 s2, s16, s0
	s_addc_u32 s3, s17, 0
	s_lshl_b32 s0, s15, 9
	s_lshl_b32 s4, s14, 1
	s_add_u32 s0, s0, s4
	s_mov_b32 s1, 0
	v_lshlrev_b32_e32 v28, 11, v0
	v_mov_b32_e32 v29, 0
	v_lshl_add_u64 v[28:29], s[2:3], 0, v[28:29]
	v_lshl_add_u64 v[28:29], v[28:29], 0, s[0:1]
	s_mov_b32 s6, 0x20000
	s_mov_b32 s7, 0
	v_lshl_add_u64 v[30:31], v[28:29], 0, s[6:7]
	v_cvt_pk_bf16_f32 v20, v4, v5
	v_cvt_pk_bf16_f32 v21, v6, v7
	v_cvt_pk_bf16_f32 v22, v8, v9
	v_cvt_pk_bf16_f32 v23, v10, v11
	v_cvt_pk_bf16_f32 v24, v12, v13
	v_cvt_pk_bf16_f32 v25, v14, v15
	v_cvt_pk_bf16_f32 v26, v16, v17
	v_cvt_pk_bf16_f32 v27, v18, v19
	global_store_dwordx4 v[28:29], v[20:23], off
	global_store_dwordx4 v[30:31], v[24:27], off
	s_barrier
